# + m16: grid barrier leader does not wait for the acknowledgement of its release add before the closing workgroup barrier
# speedup vs baseline: 1.0137x; 1.0042x over previous
; __device__ __forceinline__ unsigned xb_ld(unsigned* p)              { return __hip_atomic_load(p, __ATOMIC_RELAXED, __HIP_MEMORY_SCOPE_AGENT); }
; __device__ __forceinline__ unsigned xb_add(unsigned* p, unsigned v) { return __hip_atomic_fetch_add(p, v, __ATOMIC_RELAXED, __HIP_MEMORY_SCOPE_AGENT); }
; #define XB_SPIN(cond, bar) do { unsigned _sp = 0; while (cond) { __builtin_amdgcn_s_sleep(0); \
;     if ((++_sp & 255u) == 0u) { if (xb_ld(&(bar)[XB_TMO])) break; if (_sp > XB_SPIN_CAP) { atomicAdd(&(bar)[XB_TMO], 1u); break; } } } } while (0)
; __device__ __forceinline__ void xcd_barrier(const XcdBarrier& b) {
;     ...
;             xb_add(&bar[XB_XGEN(b.x)], 1u);
;             asm volatile("s_waitcnt vmcnt(0)" ::: "memory");
;         } else {
;             XB_SPIN(xb_ld(&bar[XB_XGEN(b.x)]) == gen, bar);
;             __builtin_amdgcn_fence(__ATOMIC_ACQUIRE, "agent");
;             asm volatile("s_waitcnt vmcnt(0)" ::: "memory");
;         }
;     }
;     __syncthreads();
.LBB0_775:
	s_or_b64 exec, exec, s[12:13]
.LBB0_776:
	s_or_b64 exec, exec, s[6:7]
	s_mov_b64 s[6:7], 0
	s_waitcnt lgkmcnt(0)
	s_barrier
